# select_row: threshold bits 22..16 searched on a packed 7-bit-digit image (4 keys per dword, guard-bit sub/and/bcnt) instead of cmp/addc per key; same T, same outputs
# speedup vs baseline: 1.0015x; 1.0015x over previous
; DI void select_row(const float* SC, unsigned* dmask, int b, int t, int lane) {
;     ...
;     unsigned T = 0u; bool hit = false; int startbit = 31;
;     {
;         int cnt; SEL_COUNT(0xBF800000u, cnt);
;         if (cnt < 256) {
; #pragma unroll 1
;             for (unsigned e = 0x7Eu; e >= 0x7Au; --e) {
;                 const unsigned cand = 0x80000000u | (e << 23); SEL_COUNT(cand, cnt);
;                 if (cnt >= 256) { T = cand; startbit = 22; hit = (cnt == 256); break; }
;             }
;         }
;     }
;     if (!hit) {
;     ...
;             const unsigned cand = T | (1u << bit); int cnt; SEL_COUNT(cand, cnt);
;             if (cnt >= 256) { T = cand; if (cnt == 256) { hit = true; break; } }
;         }
;     }
.Lsel7:
	s_add_u32 s10, s14, 0x7fffff
	s_mov_b32 s11, 0x0c0c0602
	s_mov_b32 s66, 0x06020c0c
	s_mov_b32 s67, 0x80808080
	v_min_u32_e32 v182, s10, v11
	v_min_u32_e32 v183, s10, v10
	v_min_u32_e32 v184, s10, v121
	v_min_u32_e32 v185, s10, v9
	v_sub_u32_e64 v182, v182, s14 clamp
	v_sub_u32_e64 v183, v183, s14 clamp
	v_sub_u32_e64 v184, v184, s14 clamp
	v_sub_u32_e64 v185, v185, s14 clamp
	v_perm_b32 v186, v183, v182, s11
	v_perm_b32 v187, v185, v184, s66
	v_or3_b32 v174, v186, v187, s67
	v_min_u32_e32 v182, s10, v7
	v_min_u32_e32 v183, s10, v6
	v_min_u32_e32 v184, s10, v8
	v_min_u32_e32 v185, s10, v5
	v_sub_u32_e64 v182, v182, s14 clamp
	v_sub_u32_e64 v183, v183, s14 clamp
	v_sub_u32_e64 v184, v184, s14 clamp
	v_sub_u32_e64 v185, v185, s14 clamp
	v_perm_b32 v186, v183, v182, s11
	v_perm_b32 v187, v185, v184, s66
	v_or3_b32 v175, v186, v187, s67
	s_and_b64 vcc, exec, s[82:83]
	s_cbranch_vccnz .Ls7_su1
	v_min_u32_e32 v182, s10, v33
	v_min_u32_e32 v183, s10, v41
	v_min_u32_e32 v184, s10, v32
	v_min_u32_e32 v185, s10, v42
	v_sub_u32_e64 v182, v182, s14 clamp
	v_sub_u32_e64 v183, v183, s14 clamp
	v_sub_u32_e64 v184, v184, s14 clamp
	v_sub_u32_e64 v185, v185, s14 clamp
	v_perm_b32 v186, v183, v182, s11
	v_perm_b32 v187, v185, v184, s66
	v_or3_b32 v176, v186, v187, s67
	v_min_u32_e32 v182, s10, v29
	v_min_u32_e32 v183, s10, v30
	v_min_u32_e32 v184, s10, v28
	v_min_u32_e32 v185, s10, v31
	v_sub_u32_e64 v182, v182, s14 clamp
	v_sub_u32_e64 v183, v183, s14 clamp
	v_sub_u32_e64 v184, v184, s14 clamp
	v_sub_u32_e64 v185, v185, s14 clamp
	v_perm_b32 v186, v183, v182, s11
	v_perm_b32 v187, v185, v184, s66
	v_or3_b32 v177, v186, v187, s67
.Ls7_su1:
	s_and_b64 vcc, exec, s[78:79]
	s_cbranch_vccnz .Ls7_su2
	v_min_u32_e32 v182, s10, v24
	v_min_u32_e32 v183, s10, v25
	v_min_u32_e32 v184, s10, v26
	v_min_u32_e32 v185, s10, v27
	v_sub_u32_e64 v182, v182, s14 clamp
	v_sub_u32_e64 v183, v183, s14 clamp
	v_sub_u32_e64 v184, v184, s14 clamp
	v_sub_u32_e64 v185, v185, s14 clamp
	v_perm_b32 v186, v183, v182, s11
	v_perm_b32 v187, v185, v184, s66
	v_or3_b32 v178, v186, v187, s67
	v_min_u32_e32 v182, s10, v21
	v_min_u32_e32 v183, s10, v22
	v_min_u32_e32 v184, s10, v18
	v_min_u32_e32 v185, s10, v23
	v_sub_u32_e64 v182, v182, s14 clamp
	v_sub_u32_e64 v183, v183, s14 clamp
	v_sub_u32_e64 v184, v184, s14 clamp
	v_sub_u32_e64 v185, v185, s14 clamp
	v_perm_b32 v186, v183, v182, s11
	v_perm_b32 v187, v185, v184, s66
	v_or3_b32 v179, v186, v187, s67
.Ls7_su2:
	s_and_b64 vcc, exec, s[76:77]
	s_cbranch_vccnz .Ls7_su3
	v_min_u32_e32 v182, s10, v15
	v_min_u32_e32 v183, s10, v16
	v_min_u32_e32 v184, s10, v19
	v_min_u32_e32 v185, s10, v20
	v_sub_u32_e64 v182, v182, s14 clamp
	v_sub_u32_e64 v183, v183, s14 clamp
	v_sub_u32_e64 v184, v184, s14 clamp
	v_sub_u32_e64 v185, v185, s14 clamp
	v_perm_b32 v186, v183, v182, s11
	v_perm_b32 v187, v185, v184, s66
	v_or3_b32 v180, v186, v187, s67
	v_min_u32_e32 v182, s10, v13
	v_min_u32_e32 v183, s10, v14
	v_min_u32_e32 v184, s10, v12
	v_min_u32_e32 v185, s10, v17
	v_sub_u32_e64 v182, v182, s14 clamp
	v_sub_u32_e64 v183, v183, s14 clamp
	v_sub_u32_e64 v184, v184, s14 clamp
	v_sub_u32_e64 v185, v185, s14 clamp
	v_perm_b32 v186, v183, v182, s11
	v_perm_b32 v187, v185, v184, s66
	v_or3_b32 v181, v186, v187, s67
.Ls7_su3:
	s_mov_b32 s56, 0
	s_mov_b32 s57, 6
.Ls7_loop:
	s_lshl_b32 s66, 1, s57
	s_or_b32 s66, s66, s56
	s_mul_i32 s11, s66, 0x01010101
	v_subrev_u32_e32 v186, s11, v174
	v_and_b32_e32 v186, s67, v186
	v_subrev_u32_e32 v187, s11, v175
	v_and_b32_e32 v187, s67, v187
	v_bcnt_u32_b32 v188, v186, 0
	v_bcnt_u32_b32 v188, v187, v188
	s_and_b64 vcc, exec, s[82:83]
	s_cbranch_vccnz .Ls7_pr1
	v_subrev_u32_e32 v186, s11, v176
	v_and_b32_e32 v186, s67, v186
	v_subrev_u32_e32 v187, s11, v177
	v_and_b32_e32 v187, s67, v187
	v_bcnt_u32_b32 v188, v186, v188
	v_bcnt_u32_b32 v188, v187, v188
.Ls7_pr1:
	s_and_b64 vcc, exec, s[78:79]
	s_cbranch_vccnz .Ls7_pr2
	v_subrev_u32_e32 v186, s11, v178
	v_and_b32_e32 v186, s67, v186
	v_subrev_u32_e32 v187, s11, v179
	v_and_b32_e32 v187, s67, v187
	v_bcnt_u32_b32 v188, v186, v188
	v_bcnt_u32_b32 v188, v187, v188
.Ls7_pr2:
	s_and_b64 vcc, exec, s[76:77]
	s_cbranch_vccnz .Ls7_pr3
	v_subrev_u32_e32 v186, s11, v180
	v_and_b32_e32 v186, s67, v186
	v_subrev_u32_e32 v187, s11, v181
	v_and_b32_e32 v187, s67, v187
	v_bcnt_u32_b32 v188, v186, v188
	v_bcnt_u32_b32 v188, v187, v188
.Ls7_pr3:
	s_nop 1
	v_add_u32_dpp v188, v188, v188 row_shr:1 row_mask:0xf bank_mask:0xf bound_ctrl:1
	s_nop 1
	v_add_u32_dpp v188, v188, v188 row_shr:2 row_mask:0xf bank_mask:0xf bound_ctrl:1
	s_nop 1
	v_add_u32_dpp v188, v188, v188 row_shr:4 row_mask:0xf bank_mask:0xf bound_ctrl:1
	s_nop 1
	v_add_u32_dpp v188, v188, v188 row_shr:8 row_mask:0xf bank_mask:0xf bound_ctrl:1
	s_nop 1
	v_add_u32_dpp v188, v188, v188 row_bcast:15 row_mask:0xa bank_mask:0xf
	s_nop 1
	v_add_u32_dpp v188, v188, v188 row_bcast:31 row_mask:0xc bank_mask:0xf
	s_nop 1
	v_readlane_b32 s10, v188, 63
	s_cmpk_lt_i32 s10, 0x100
	s_cbranch_scc1 .Ls7_rej
	s_mov_b32 s56, s66
	s_cmpk_eq_i32 s10, 0x100
	s_cbranch_scc1 .Ls7_hit
.Ls7_rej:
	s_add_i32 s57, s57, -1
	s_cmp_ge_i32 s57, 0
	s_cbranch_scc1 .Ls7_loop
	s_lshl_b32 s56, s56, 16
	s_or_b32 s14, s14, s56
	s_mov_b32 s80, 15
	s_branch .LBB0_571
.Ls7_hit:
	s_lshl_b32 s56, s56, 16
	s_or_b32 s14, s14, s56
	v_mov_b32_e32 v2, s14
	s_mov_b64 s[8:9], -1
	s_branch .LBB0_582
